# attention: next-tile LDS-DMA issue interleaved into the QK MFMA stream (fast path)
# speedup vs baseline: 1.0504x; 1.0031x over previous
.LBB0_621:
	s_add_i32 s25, s24, 1
	s_cmp_lg_u32 s24, 2
	s_cselect_b32 s35, s25, 0
	s_add_i32 s25, s72, 1
	s_cmp_ge_u32 s25, s31
	s_cbranch_scc1 .LBB0_625
	s_sub_i32 s73, s18, 63
	s_cmp_gt_i32 s73, s27
	s_cbranch_scc1 .Lslow_dma_0
	s_bitcmp1_b32 s72, 0
	s_cselect_b32 s72, 0x2400, 0
	v_add_u32_e32 v32, s72, v188
	s_setprio 1
	ds_read_b128 v[214:217], v32
	ds_read_b128 v[218:221], v32 offset:4608
	ds_read_b128 v[222:225], v32 offset:32
	ds_read_b128 v[226:229], v32 offset:4640
	ds_read_b128 v[230:233], v32 offset:64
	ds_read_b128 v[234:237], v32 offset:4672
	ds_read_b128 v[238:241], v32 offset:96
	ds_read_b128 v[244:247], v32 offset:4704
	s_waitcnt lgkmcnt(7)
	v_mfma_f32_32x32x16_bf16 v[114:129], v[214:217], v[146:149], v[98:113]
	s_waitcnt lgkmcnt(6)
	v_mfma_f32_32x32x16_bf16 v[130:145], v[218:221], v[146:149], v[98:113]
	s_bitcmp1_b32 s25, 0
	s_cselect_b32 s73, 0x2400, 0
	s_add_i32 s74, s73, s5
	v_lshl_add_u64 v[252:253], s[70:71], 0, v[170:171]
	s_add_i32 s74, s74, 0
	s_mov_b32 s75, m0
	s_mov_b32 m0, s74
	s_nop 0
	global_load_lds_dwordx4 v[252:253], off
	s_mov_b32 m0, s75
	s_waitcnt lgkmcnt(5)
	v_mfma_f32_32x32x16_bf16 v[114:129], v[222:225], v[150:153], v[114:129]
	s_andn2_b64 vcc, exec, s[10:11]
	s_cbranch_vccnz .LBB0_624_f
	s_add_i32 s73, s73, s80
	v_lshl_add_u64 v[252:253], s[70:71], 0, v[176:177]
	s_add_i32 s73, s73, 0
	s_mov_b32 s74, m0
	s_mov_b32 m0, s73
	s_nop 0
	global_load_lds_dwordx4 v[252:253], off
	s_mov_b32 m0, s74
.LBB0_624_f:
	s_waitcnt lgkmcnt(4)
	v_mfma_f32_32x32x16_bf16 v[130:145], v[226:229], v[150:153], v[130:145]
	s_add_u32 s74, s70, 0x4000000
	s_mul_i32 s73, s35, 0x5000
	s_addc_u32 s75, s71, 0
	s_add_i32 s73, s26, s73
	v_lshl_add_u64 v[252:253], s[74:75], 0, v[172:173]
	s_add_i32 s73, s73, 0
	s_mov_b32 vcc_lo, m0
	s_mov_b32 m0, s73
	s_nop 0
	global_load_lds_dwordx4 v[252:253], off
	s_mov_b32 m0, vcc_lo
	s_waitcnt lgkmcnt(3)
	v_mfma_f32_32x32x16_bf16 v[114:129], v[230:233], v[154:157], v[114:129]
	s_add_i32 vcc_lo, s73, 0x2000
	v_lshl_add_u64 v[252:253], s[74:75], 0, v[174:175]
	s_mov_b32 vcc_hi, m0
	s_mov_b32 m0, vcc_lo
	s_nop 0
	global_load_lds_dwordx4 v[252:253], off
	s_mov_b32 m0, vcc_hi
	s_waitcnt lgkmcnt(2)
	v_mfma_f32_32x32x16_bf16 v[130:145], v[234:237], v[154:157], v[130:145]
	v_readfirstlane_b32 s32, v242
	s_cmpk_gt_u32 s32, 0xff
	s_cbranch_scc1 .Lskip_v2_0_f
	v_lshl_add_u64 v[252:253], s[74:75], 0, v[178:179]
	s_addk_i32 s73, 0x4000
	s_mov_b32 s74, m0
	s_mov_b32 m0, s73
	s_nop 0
	global_load_lds_dwordx4 v[252:253], off
	s_mov_b32 m0, s74
.Lskip_v2_0_f:
	s_waitcnt lgkmcnt(1)
	v_mfma_f32_32x32x16_bf16 v[114:129], v[238:241], v[158:161], v[114:129]
	s_waitcnt lgkmcnt(0)
	v_mfma_f32_32x32x16_bf16 v[130:145], v[244:247], v[158:161], v[130:145]
	s_setprio 0
	s_branch .Lfast_join_0
.Lslow_dma_0:
	s_bitcmp1_b32 s25, 0
	s_cselect_b32 s73, 0x2400, 0
	s_add_i32 s74, s73, s5
	v_lshl_add_u64 v[114:115], s[70:71], 0, v[170:171]
	s_add_i32 s74, s74, 0
	s_mov_b32 s75, m0
	s_mov_b32 m0, s74
	s_nop 0
	global_load_lds_dwordx4 v[114:115], off
	s_mov_b32 m0, s75
	s_andn2_b64 vcc, exec, s[10:11]
	s_cbranch_vccnz .LBB0_624
	s_add_i32 s73, s73, s80
	v_lshl_add_u64 v[114:115], s[70:71], 0, v[176:177]
	s_add_i32 s73, s73, 0
	s_mov_b32 s74, m0
	s_mov_b32 m0, s73
	s_nop 0
	global_load_lds_dwordx4 v[114:115], off
	s_mov_b32 m0, s74

.Lfast_join_0:
	s_cmp_le_i32 s18, s76
	s_cbranch_scc1 .LBB0_628
	v_add_u32_e32 v32, s18, v190
	v_subrev_u32_e32 v200, 31, v32
	v_subrev_u32_e32 v198, 63, v32
	v_cmp_le_i32_e32 vcc, v200, v166
	s_nop 4
	v_cndmask_b32_e32 v130, v208, v130, vcc
	v_cmp_lt_i32_e32 vcc, v198, v166
	s_nop 1
	v_cndmask_b32_e32 v115, v208, v115, vcc
	v_cmp_le_i32_e32 vcc, v198, v166
	v_subrev_u32_e32 v198, 30, v32
	s_nop 0
	v_cndmask_b32_e32 v114, v208, v114, vcc
	v_cmp_le_i32_e32 vcc, v198, v166
	v_subrev_u32_e32 v198, 61, v32
	s_nop 0
	v_cndmask_b32_e32 v131, v208, v131, vcc
	v_cmp_le_i32_e32 vcc, v198, v166
	v_subrev_u32_e32 v198, 29, v32
	s_nop 0
	v_cndmask_b32_e32 v116, v208, v116, vcc
	v_cmp_le_i32_e32 vcc, v198, v166
	v_subrev_u32_e32 v198, 60, v32
	s_nop 0
	v_cndmask_b32_e32 v132, v208, v132, vcc
	v_cmp_le_i32_e32 vcc, v198, v166
	v_subrev_u32_e32 v198, 28, v32
	s_nop 0
	v_cndmask_b32_e32 v117, v208, v117, vcc
	v_cmp_le_i32_e32 vcc, v198, v166
	v_subrev_u32_e32 v198, 55, v32
	s_nop 0
	v_cndmask_b32_e32 v133, v208, v133, vcc
	v_cmp_le_i32_e32 vcc, v198, v166
	v_subrev_u32_e32 v198, 23, v32
	s_nop 0
	v_cndmask_b32_e32 v118, v208, v118, vcc
	v_cmp_le_i32_e32 vcc, v198, v166
	v_subrev_u32_e32 v198, 54, v32
	s_nop 0
	v_cndmask_b32_e32 v134, v208, v134, vcc
	v_cmp_le_i32_e32 vcc, v198, v166
	v_subrev_u32_e32 v198, 22, v32
	s_nop 0
	v_cndmask_b32_e32 v119, v208, v119, vcc
	v_cmp_le_i32_e32 vcc, v198, v166
	v_subrev_u32_e32 v198, 53, v32
	s_nop 0
	v_cndmask_b32_e32 v135, v208, v135, vcc
	v_cmp_le_i32_e32 vcc, v198, v166
	v_subrev_u32_e32 v198, 21, v32
	s_nop 0
	v_cndmask_b32_e32 v120, v208, v120, vcc
	v_cmp_le_i32_e32 vcc, v198, v166
	v_subrev_u32_e32 v198, 52, v32
	s_nop 0
	v_cndmask_b32_e32 v136, v208, v136, vcc
	v_cmp_le_i32_e32 vcc, v198, v166
	v_subrev_u32_e32 v198, 20, v32
	s_nop 0
	v_cndmask_b32_e32 v121, v208, v121, vcc
	v_cmp_le_i32_e32 vcc, v198, v166
	v_subrev_u32_e32 v198, 47, v32
	s_nop 0
	v_cndmask_b32_e32 v137, v208, v137, vcc
	v_cmp_le_i32_e32 vcc, v198, v166
	v_add_u32_e32 v198, -15, v32
	s_nop 0
	v_cndmask_b32_e32 v122, v208, v122, vcc
	v_cmp_le_i32_e32 vcc, v198, v166
	v_subrev_u32_e32 v198, 46, v32
	s_nop 0
	v_cndmask_b32_e32 v138, v208, v138, vcc
	v_cmp_le_i32_e32 vcc, v198, v166
	v_add_u32_e32 v198, -14, v32
	s_nop 0
	v_cndmask_b32_e32 v123, v208, v123, vcc
	v_cmp_le_i32_e32 vcc, v198, v166
	v_subrev_u32_e32 v198, 45, v32
	s_nop 0
	v_cndmask_b32_e32 v139, v208, v139, vcc
	v_cmp_le_i32_e32 vcc, v198, v166
	v_add_u32_e32 v198, -13, v32
	s_nop 0
	v_cndmask_b32_e32 v124, v208, v124, vcc
	v_cmp_le_i32_e32 vcc, v198, v166
	v_subrev_u32_e32 v198, 44, v32
	s_nop 0
	v_cndmask_b32_e32 v140, v208, v140, vcc
	v_cmp_le_i32_e32 vcc, v198, v166
	v_add_u32_e32 v198, -12, v32
	s_nop 0
	v_cndmask_b32_e32 v125, v208, v125, vcc
	v_cmp_le_i32_e32 vcc, v198, v166
	v_subrev_u32_e32 v198, 39, v32
	s_nop 0
	v_cndmask_b32_e32 v141, v208, v141, vcc
	v_cmp_le_i32_e32 vcc, v198, v166
	v_add_u32_e32 v198, -7, v32
	s_nop 0
	v_cndmask_b32_e32 v126, v208, v126, vcc
	v_cmp_le_i32_e32 vcc, v198, v166
	v_subrev_u32_e32 v198, 38, v32
	s_nop 0
	v_cndmask_b32_e32 v142, v208, v142, vcc
	v_cmp_le_i32_e32 vcc, v198, v166
	v_add_u32_e32 v198, -6, v32
	s_nop 0
	v_cndmask_b32_e32 v127, v208, v127, vcc
	v_cmp_le_i32_e32 vcc, v198, v166
	v_subrev_u32_e32 v198, 37, v32
	s_nop 0
	v_cndmask_b32_e32 v143, v208, v143, vcc
	v_cmp_le_i32_e32 vcc, v198, v166
	v_add_u32_e32 v198, -5, v32
	s_nop 0
	v_cndmask_b32_e32 v128, v208, v128, vcc
	v_cmp_le_i32_e32 vcc, v198, v166
	v_subrev_u32_e32 v198, 36, v32
	v_add_u32_e32 v32, -4, v32
	v_cndmask_b32_e32 v144, v208, v144, vcc
	v_cmp_le_i32_e32 vcc, v198, v166
	s_nop 1
	v_cndmask_b32_e32 v129, v208, v129, vcc
	v_cmp_le_i32_e32 vcc, v32, v166
	s_nop 1
	v_cndmask_b32_e32 v145, v208, v145, vcc

.LBB0_821:
	s_add_i32 s24, s35, 1
	s_cmp_lg_u32 s35, 2
	s_cselect_b32 s24, s24, 0
	s_add_i32 s25, s72, 1
	s_cmp_ge_u32 s25, s31
	s_cbranch_scc1 .LBB0_825
	s_sub_i32 s73, s18, 63
	s_cmp_gt_i32 s73, s26
	s_cbranch_scc1 .Lslow_dma_1
	s_bitcmp1_b32 s72, 0
	s_cselect_b32 s72, 0x2400, 0
	v_add_u32_e32 v32, s72, v188
	s_setprio 1
	ds_read_b128 v[214:217], v32
	ds_read_b128 v[218:221], v32 offset:4608
	ds_read_b128 v[222:225], v32 offset:32
	ds_read_b128 v[226:229], v32 offset:4640
	ds_read_b128 v[230:233], v32 offset:64
	ds_read_b128 v[234:237], v32 offset:4672
	ds_read_b128 v[238:241], v32 offset:96
	ds_read_b128 v[244:247], v32 offset:4704
	s_waitcnt lgkmcnt(7)
	v_mfma_f32_32x32x16_bf16 v[114:129], v[214:217], v[146:149], v[98:113]
	s_waitcnt lgkmcnt(6)
	v_mfma_f32_32x32x16_bf16 v[130:145], v[218:221], v[146:149], v[98:113]
	s_bitcmp1_b32 s25, 0
	s_cselect_b32 s73, 0x2400, 0
	s_add_i32 s74, s73, s3
	v_lshl_add_u64 v[252:253], s[70:71], 0, v[170:171]
	s_add_i32 s74, s74, 0
	s_mov_b32 s75, m0
	s_mov_b32 m0, s74
	s_nop 0
	global_load_lds_dwordx4 v[252:253], off
	s_mov_b32 m0, s75
	s_waitcnt lgkmcnt(5)
	v_mfma_f32_32x32x16_bf16 v[114:129], v[222:225], v[150:153], v[114:129]
	s_andn2_b64 vcc, exec, s[10:11]
	s_cbranch_vccnz .LBB0_824_f
	s_add_i32 s73, s73, s27
	v_lshl_add_u64 v[252:253], s[70:71], 0, v[176:177]
	s_add_i32 s73, s73, 0
	s_mov_b32 s74, m0
	s_mov_b32 m0, s73
	s_nop 0
	global_load_lds_dwordx4 v[252:253], off
	s_mov_b32 m0, s74
.LBB0_824_f:
	s_waitcnt lgkmcnt(4)
	v_mfma_f32_32x32x16_bf16 v[130:145], v[226:229], v[150:153], v[130:145]
	s_add_u32 s74, s70, 0x3ffff80
	s_mul_i32 s73, s24, 0x5000
	s_addc_u32 s75, s71, 0
	s_add_i32 s73, s5, s73
	v_lshl_add_u64 v[252:253], s[74:75], 0, v[172:173]
	s_add_i32 s73, s73, 0
	s_mov_b32 vcc_lo, m0
	s_mov_b32 m0, s73
	s_nop 0
	global_load_lds_dwordx4 v[252:253], off
	s_mov_b32 m0, vcc_lo
	s_waitcnt lgkmcnt(3)
	v_mfma_f32_32x32x16_bf16 v[114:129], v[230:233], v[154:157], v[114:129]
	s_add_i32 vcc_lo, s73, 0x2000
	v_lshl_add_u64 v[252:253], s[74:75], 0, v[174:175]
	s_mov_b32 vcc_hi, m0
	s_mov_b32 m0, vcc_lo
	s_nop 0
	global_load_lds_dwordx4 v[252:253], off
	s_mov_b32 m0, vcc_hi
	s_waitcnt lgkmcnt(2)
	v_mfma_f32_32x32x16_bf16 v[130:145], v[234:237], v[154:157], v[130:145]
	v_readfirstlane_b32 s32, v242
	s_cmpk_gt_u32 s32, 0xff
	s_cbranch_scc1 .Lskip_v2_1_f
	v_lshl_add_u64 v[252:253], s[74:75], 0, v[178:179]
	s_addk_i32 s73, 0x4000
	s_mov_b32 s74, m0
	s_mov_b32 m0, s73
	s_nop 0
	global_load_lds_dwordx4 v[252:253], off
	s_mov_b32 m0, s74

; template <int DQK>
; __device__ __forceinline__ void attn_pass4(LAS unsigned char* lds, const bf16* Qp, int qpitch, const bf16* Kp, int kpitch, const bf16* Vp, int vpitch, int q0, f32x16 (&o)[4], float (&rl)[16]) {
;     ...
;             if (t + 1 < NT) ATT_DMA(t + 1, (t + 1) & 1, vnext);
.Lslow_dma_1:
	s_bitcmp1_b32 s25, 0
	s_cselect_b32 s73, 0x2400, 0
	s_add_i32 s74, s73, s3
	v_lshl_add_u64 v[114:115], s[70:71], 0, v[170:171]
	s_add_i32 s74, s74, 0
	s_mov_b32 s75, m0
	s_mov_b32 m0, s74
	s_nop 0
	global_load_lds_dwordx4 v[114:115], off
	s_mov_b32 m0, s75
	s_andn2_b64 vcc, exec, s[10:11]
	s_cbranch_vccnz .LBB0_824
	s_add_i32 s73, s73, s27
	v_lshl_add_u64 v[114:115], s[70:71], 0, v[176:177]
	s_add_i32 s73, s73, 0
	s_mov_b32 s74, m0
	s_mov_b32 m0, s73
	s_nop 0
	global_load_lds_dwordx4 v[114:115], off
	s_mov_b32 m0, s74

.LBB0_2151:
	s_add_i32 s61, s78, 1
	s_cmp_lg_u32 s78, 2
	s_cselect_b32 s76, s61, 0
	s_add_i32 s77, s60, 1
	s_cmp_ge_u32 s77, s69
	s_cbranch_scc1 .LBB0_2155
	s_sub_i32 s61, s75, 63
	s_cmp_gt_i32 s61, s25
	s_cbranch_scc1 .Lslow_dma_2
	s_bitcmp1_b32 s60, 0
	s_cselect_b32 s60, 0x6400, 0
	v_add_u32_e32 v0, s60, v200
	s_setprio 1
	ds_read_b128 v[214:217], v0
	ds_read_b128 v[218:221], v0 offset:32
	ds_read_b128 v[222:225], v0 offset:12800
	ds_read_b128 v[226:229], v0 offset:12832
	ds_read_b128 v[230:233], v0 offset:64
	ds_read_b128 v[234:237], v0 offset:12864
	ds_read_b128 v[238:241], v0 offset:96
	ds_read_b128 v[244:247], v0 offset:12896
	ds_read_b128 v[248:251], v0 offset:128
	s_waitcnt lgkmcnt(8)
	v_mfma_f32_32x32x16_bf16 v[96:111], v[214:217], v[128:131], v[80:95]
	ds_read_b128 v[214:217], v0 offset:12928
	s_waitcnt lgkmcnt(8)
	v_mfma_f32_32x32x16_bf16 v[96:111], v[218:221], v[132:135], v[96:111]
	ds_read_b128 v[218:221], v0 offset:160
	s_bitcmp1_b32 s77, 0
	s_cselect_b32 s61, 0x6400, 0
	s_add_i32 s62, s61, s2
	s_add_i32 s62, s62, 0
	v_lshl_add_u64 v[252:253], s[56:57], 0, v[180:181]
	s_mov_b32 s63, m0
	s_mov_b32 m0, s62
	s_nop 0
	global_load_lds_dwordx4 v[252:253], off
	s_mov_b32 m0, s63
	s_waitcnt lgkmcnt(8)
	v_mfma_f32_32x32x16_bf16 v[112:127], v[222:225], v[128:131], v[80:95]
	ds_read_b128 v[222:225], v0 offset:12960
	s_waitcnt lgkmcnt(8)
	v_mfma_f32_32x32x16_bf16 v[112:127], v[226:229], v[132:135], v[112:127]
	ds_read_b128 v[226:229], v0 offset:192
	s_waitcnt lgkmcnt(8)
	v_mfma_f32_32x32x16_bf16 v[96:111], v[230:233], v[136:139], v[96:111]
	ds_read_b128 v[230:233], v0 offset:12992
	s_add_i32 s62, s61, s72
	s_add_i32 s62, s62, 0
	v_lshl_add_u64 v[252:253], s[56:57], 0, v[182:183]
	s_mov_b32 s63, m0
	s_mov_b32 m0, s62
	s_nop 0
	global_load_lds_dwordx4 v[252:253], off
	s_mov_b32 m0, s63
	s_waitcnt lgkmcnt(8)
	v_mfma_f32_32x32x16_bf16 v[112:127], v[234:237], v[136:139], v[112:127]
	ds_read_b128 v[234:237], v0 offset:224
	s_waitcnt lgkmcnt(8)
	v_mfma_f32_32x32x16_bf16 v[96:111], v[238:241], v[140:143], v[96:111]
	ds_read_b128 v[238:241], v0 offset:13024
	s_waitcnt lgkmcnt(8)
	v_mfma_f32_32x32x16_bf16 v[112:127], v[244:247], v[140:143], v[112:127]
	ds_read_b128 v[244:247], v0 offset:256
	s_add_i32 s62, s61, s73
	v_lshl_add_u64 v[252:253], s[56:57], 0, v[184:185]
	s_add_i32 s62, s62, 0
	s_mov_b32 s63, m0
	s_mov_b32 m0, s62
	s_nop 0
	global_load_lds_dwordx4 v[252:253], off
	s_mov_b32 m0, s63
	s_waitcnt lgkmcnt(8)
	v_mfma_f32_32x32x16_bf16 v[96:111], v[248:251], v[144:147], v[96:111]
	ds_read_b128 v[248:251], v0 offset:13056
	s_waitcnt lgkmcnt(8)
	v_mfma_f32_32x32x16_bf16 v[112:127], v[214:217], v[144:147], v[112:127]
	ds_read_b128 v[214:217], v0 offset:288
	s_waitcnt lgkmcnt(8)
	v_mfma_f32_32x32x16_bf16 v[96:111], v[218:221], v[148:151], v[96:111]
	ds_read_b128 v[218:221], v0 offset:13088
	s_andn2_b64 vcc, exec, s[12:13]
	s_cbranch_vccnz .LBB0_2154_f
	s_add_i32 s61, s61, s74
	v_lshl_add_u64 v[252:253], s[56:57], 0, v[190:191]
	s_add_i32 s61, s61, 0
	s_mov_b32 s62, m0
	s_mov_b32 m0, s61
	s_nop 0
	global_load_lds_dwordx4 v[252:253], off
	s_mov_b32 m0, s62
.LBB0_2154_f:
	s_waitcnt lgkmcnt(8)
	v_mfma_f32_32x32x16_bf16 v[112:127], v[222:225], v[148:151], v[112:127]
	ds_read_b128 v[222:225], v0 offset:320
	s_waitcnt lgkmcnt(8)
	v_mfma_f32_32x32x16_bf16 v[96:111], v[226:229], v[152:155], v[96:111]
	ds_read_b128 v[226:229], v0 offset:13120
	s_waitcnt lgkmcnt(8)
	v_mfma_f32_32x32x16_bf16 v[112:127], v[230:233], v[152:155], v[112:127]
	ds_read_b128 v[230:233], v0 offset:352
	s_mul_i32 s61, s76, 0x5000
	s_add_i32 s61, s24, s61
	v_lshl_add_u64 v[252:253], s[58:59], 0, v[186:187]
	s_add_i32 s61, s61, 0
	s_mov_b32 s62, m0
	s_mov_b32 m0, s61
	s_nop 0
	global_load_lds_dwordx4 v[252:253], off
	s_mov_b32 m0, s62
	s_waitcnt lgkmcnt(8)
	v_mfma_f32_32x32x16_bf16 v[96:111], v[234:237], v[156:159], v[96:111]
	ds_read_b128 v[234:237], v0 offset:13152
	s_waitcnt lgkmcnt(8)
	v_mfma_f32_32x32x16_bf16 v[112:127], v[238:241], v[156:159], v[112:127]
	s_waitcnt lgkmcnt(7)
	v_mfma_f32_32x32x16_bf16 v[96:111], v[244:247], v[160:163], v[96:111]
	v_lshl_add_u64 v[252:253], s[58:59], 0, v[188:189]
	s_add_i32 s62, s61, 0x2000
	s_mov_b32 s63, m0
	s_mov_b32 m0, s62
	s_nop 0
	global_load_lds_dwordx4 v[252:253], off
	s_mov_b32 m0, s63
	s_waitcnt lgkmcnt(6)
	v_mfma_f32_32x32x16_bf16 v[112:127], v[248:251], v[160:163], v[112:127]
	s_waitcnt lgkmcnt(5)
	v_mfma_f32_32x32x16_bf16 v[96:111], v[214:217], v[164:167], v[96:111]
	s_waitcnt lgkmcnt(4)
	v_mfma_f32_32x32x16_bf16 v[112:127], v[218:221], v[164:167], v[112:127]
	v_readfirstlane_b32 s32, v242
	s_cmpk_gt_u32 s32, 0xff
	s_cbranch_scc1 .Lskip_v2_2_f
	v_lshl_add_u64 v[252:253], s[58:59], 0, v[192:193]
	s_addk_i32 s61, 0x4000
	s_mov_b32 s62, m0
	s_mov_b32 m0, s61
	s_nop 0
	global_load_lds_dwordx4 v[252:253], off
	s_mov_b32 m0, s62
.Lskip_v2_2_f:
	s_waitcnt lgkmcnt(3)
	v_mfma_f32_32x32x16_bf16 v[96:111], v[222:225], v[168:171], v[96:111]
	s_waitcnt lgkmcnt(2)
	v_mfma_f32_32x32x16_bf16 v[112:127], v[226:229], v[168:171], v[112:127]
	s_waitcnt lgkmcnt(1)
	v_mfma_f32_32x32x16_bf16 v[96:111], v[230:233], v[172:175], v[96:111]
	s_waitcnt lgkmcnt(0)
	v_mfma_f32_32x32x16_bf16 v[112:127], v[234:237], v[172:175], v[112:127]
	s_setprio 0
	s_branch .Lfast_join_2
.Lslow_dma_2:
	s_bitcmp1_b32 s77, 0
	s_cselect_b32 s61, 0x6400, 0
	s_add_i32 s62, s61, s2
	s_add_i32 s62, s62, 0
	v_lshl_add_u64 v[4:5], s[56:57], 0, v[180:181]
	s_mov_b32 s63, m0
	s_mov_b32 m0, s62
	s_nop 0
	global_load_lds_dwordx4 v[4:5], off
	s_mov_b32 m0, s63
	s_add_i32 s62, s61, s72
	s_add_i32 s62, s62, 0
	v_lshl_add_u64 v[4:5], s[56:57], 0, v[182:183]
	s_mov_b32 s63, m0
	s_mov_b32 m0, s62
	s_nop 0
	global_load_lds_dwordx4 v[4:5], off
	s_mov_b32 m0, s63
	s_add_i32 s62, s61, s73
	v_lshl_add_u64 v[4:5], s[56:57], 0, v[184:185]
	s_add_i32 s62, s62, 0
	s_mov_b32 s63, m0
	s_mov_b32 m0, s62
	s_nop 0
	global_load_lds_dwordx4 v[4:5], off
	s_mov_b32 m0, s63
	s_andn2_b64 vcc, exec, s[12:13]
	s_cbranch_vccnz .LBB0_2154
	s_add_i32 s61, s61, s74
	v_lshl_add_u64 v[4:5], s[56:57], 0, v[190:191]
	s_add_i32 s61, s61, 0
	s_mov_b32 s62, m0
	s_mov_b32 m0, s61
	s_nop 0
	global_load_lds_dwordx4 v[4:5], off
	s_mov_b32 m0, s62

.Lfast_join_2:
	s_cmp_le_i32 s75, s68
	s_cbranch_scc1 .LBB0_2158
	v_add_u32_e32 v0, s75, v201
	v_subrev_u32_e32 v4, 31, v0
	v_subrev_u32_e32 v3, 63, v0
	v_cmp_le_i32_e32 vcc, v4, v197
	s_nop 4
	v_cndmask_b32_e32 v112, v194, v112, vcc
	v_cmp_lt_i32_e32 vcc, v3, v197
	s_nop 1
	v_cndmask_b32_e32 v97, v194, v97, vcc
	v_cmp_le_i32_e32 vcc, v3, v197
	v_subrev_u32_e32 v3, 30, v0
	s_nop 0
	v_cndmask_b32_e32 v96, v194, v96, vcc
	v_cmp_le_i32_e32 vcc, v3, v197
	v_subrev_u32_e32 v3, 61, v0
	s_nop 0
	v_cndmask_b32_e32 v113, v194, v113, vcc
	v_cmp_le_i32_e32 vcc, v3, v197
	v_subrev_u32_e32 v3, 29, v0
	s_nop 0
	v_cndmask_b32_e32 v98, v194, v98, vcc
	v_cmp_le_i32_e32 vcc, v3, v197
	v_subrev_u32_e32 v3, 60, v0
	s_nop 0
	v_cndmask_b32_e32 v114, v194, v114, vcc
	v_cmp_le_i32_e32 vcc, v3, v197
	v_subrev_u32_e32 v3, 28, v0
	s_nop 0
	v_cndmask_b32_e32 v99, v194, v99, vcc
	v_cmp_le_i32_e32 vcc, v3, v197
	v_subrev_u32_e32 v3, 55, v0
	s_nop 0
	v_cndmask_b32_e32 v115, v194, v115, vcc
	v_cmp_le_i32_e32 vcc, v3, v197
	v_subrev_u32_e32 v3, 23, v0
	s_nop 0
	v_cndmask_b32_e32 v100, v194, v100, vcc
	v_cmp_le_i32_e32 vcc, v3, v197
	v_subrev_u32_e32 v3, 54, v0
	s_nop 0
	v_cndmask_b32_e32 v116, v194, v116, vcc
	v_cmp_le_i32_e32 vcc, v3, v197
	v_subrev_u32_e32 v3, 22, v0
	s_nop 0
	v_cndmask_b32_e32 v101, v194, v101, vcc
	v_cmp_le_i32_e32 vcc, v3, v197
	v_subrev_u32_e32 v3, 53, v0
	s_nop 0
	v_cndmask_b32_e32 v117, v194, v117, vcc
	v_cmp_le_i32_e32 vcc, v3, v197
	v_subrev_u32_e32 v3, 21, v0
	s_nop 0
	v_cndmask_b32_e32 v102, v194, v102, vcc
	v_cmp_le_i32_e32 vcc, v3, v197
	v_subrev_u32_e32 v3, 52, v0
	s_nop 0
	v_cndmask_b32_e32 v118, v194, v118, vcc
	v_cmp_le_i32_e32 vcc, v3, v197
	v_subrev_u32_e32 v3, 20, v0
	s_nop 0
	v_cndmask_b32_e32 v103, v194, v103, vcc
	v_cmp_le_i32_e32 vcc, v3, v197
	v_subrev_u32_e32 v3, 47, v0
	s_nop 0
	v_cndmask_b32_e32 v119, v194, v119, vcc
	v_cmp_le_i32_e32 vcc, v3, v197
	v_add_u32_e32 v3, -15, v0
	s_nop 0
	v_cndmask_b32_e32 v104, v194, v104, vcc
	v_cmp_le_i32_e32 vcc, v3, v197
	v_subrev_u32_e32 v3, 46, v0
	s_nop 0
	v_cndmask_b32_e32 v120, v194, v120, vcc
	v_cmp_le_i32_e32 vcc, v3, v197
	v_add_u32_e32 v3, -14, v0
	s_nop 0
	v_cndmask_b32_e32 v105, v194, v105, vcc
	v_cmp_le_i32_e32 vcc, v3, v197
	v_subrev_u32_e32 v3, 45, v0
	s_nop 0
	v_cndmask_b32_e32 v121, v194, v121, vcc
	v_cmp_le_i32_e32 vcc, v3, v197
	v_add_u32_e32 v3, -13, v0
	s_nop 0
	v_cndmask_b32_e32 v106, v194, v106, vcc
	v_cmp_le_i32_e32 vcc, v3, v197
	v_subrev_u32_e32 v3, 44, v0
	s_nop 0
	v_cndmask_b32_e32 v122, v194, v122, vcc
	v_cmp_le_i32_e32 vcc, v3, v197
	v_add_u32_e32 v3, -12, v0
	s_nop 0
	v_cndmask_b32_e32 v107, v194, v107, vcc
	v_cmp_le_i32_e32 vcc, v3, v197
	v_subrev_u32_e32 v3, 39, v0
	s_nop 0
	v_cndmask_b32_e32 v123, v194, v123, vcc
	v_cmp_le_i32_e32 vcc, v3, v197
	v_add_u32_e32 v3, -7, v0
	s_nop 0
	v_cndmask_b32_e32 v108, v194, v108, vcc
	v_cmp_le_i32_e32 vcc, v3, v197
	v_subrev_u32_e32 v3, 38, v0
	s_nop 0
	v_cndmask_b32_e32 v124, v194, v124, vcc
	v_cmp_le_i32_e32 vcc, v3, v197
	v_add_u32_e32 v3, -6, v0
	s_nop 0
	v_cndmask_b32_e32 v109, v194, v109, vcc
	v_cmp_le_i32_e32 vcc, v3, v197
	v_subrev_u32_e32 v3, 37, v0
	s_nop 0
	v_cndmask_b32_e32 v125, v194, v125, vcc
	v_cmp_le_i32_e32 vcc, v3, v197
	v_add_u32_e32 v3, -5, v0
	s_nop 0
	v_cndmask_b32_e32 v110, v194, v110, vcc
	v_cmp_le_i32_e32 vcc, v3, v197
	v_subrev_u32_e32 v3, 36, v0
	v_add_u32_e32 v0, -4, v0
	v_cndmask_b32_e32 v126, v194, v126, vcc
	v_cmp_le_i32_e32 vcc, v3, v197
	s_nop 1
	v_cndmask_b32_e32 v111, v194, v111, vcc
	v_cmp_le_i32_e32 vcc, v0, v197
	s_nop 1
	v_cndmask_b32_e32 v127, v194, v127, vcc
